# v58: v53 with back-to-back polling (no s_sleep between polls) in the grid-barrier spin loops
# baseline (speedup 1.0000x reference)
; __device__ __forceinline__ unsigned xb_ld(unsigned* p)              { return __hip_atomic_load(p, __ATOMIC_RELAXED, __HIP_MEMORY_SCOPE_AGENT); }
; #define XB_SPIN(cond, bar) do { unsigned _sp = 0; while (cond) { __builtin_amdgcn_s_sleep(1); \
;     if ((++_sp & 255u) == 0u) { if (xb_ld(&(bar)[XB_TMO])) break; if (_sp > XB_SPIN_CAP) { atomicAdd(&(bar)[XB_TMO], 1u); break; } } } } while (0)
; __device__ __forceinline__ void xcd_barrier(const XcdBarrier& b) {
;     ...
;             XB_SPIN(xb_ld(&bar[XB_XGEN(b.x)]) == gen, bar);
.Lxb0_spin:
	global_load_dword v255, v254, s[68:69] sc1
	s_waitcnt vmcnt(0)
	v_readfirstlane_b32 vcc_lo, v255
	s_cmp_ge_u32 vcc_lo, s98
	s_cbranch_scc1 .Lxb0_done
	s_nop 0
	s_add_u32 s99, s99, 1
	s_cmp_lt_u32 s99, 0x4000
	s_cbranch_scc1 .Lxb0_spin
